# phase 7 work-queue order: NSA-compressed items interleaved with the heaviest MLA items (bijective remap of the fetched index) so co-resident workgroups run different item kinds
# baseline (speedup 1.0000x reference)
.LBB0_234:
	s_or_b64 exec, exec, s[0:1]
	s_waitcnt lgkmcnt(0)
	s_barrier
	ds_read_b32 v0, v223
	s_movk_i32 s0, 0x13f
	s_waitcnt lgkmcnt(0)
	v_cmp_lt_i32_e32 vcc, s0, v0
	v_readfirstlane_b32 s12, v0
	s_mov_b64 s[0:1], -1
	s_cbranch_vccnz .LBB0_229
	s_cmp_lt_u32 s12, 0x80
	s_cbranch_scc0 .Lq7_keep
	s_lshr_b32 s98, s12, 1
	s_bitcmp1_b32 s12, 0
	s_cselect_b32 s99, 64, 0
	s_add_i32 s12, s98, s99
.Lq7_keep:
	s_cmp_gt_i32 s12, 63
	s_cbranch_scc0 .LBB0_278
	v_mov_b32_e32 v0, v222
	v_mov_b32_e32 v2, v222
	s_sub_i32 s0, s12, 64
	s_lshr_b32 s10, s0, 2
	v_ashrrev_i32_e32 v2, 1, v2
	s_sub_i32 s0, 63, s10
	v_and_b32_e32 v2, 0xffffffe0, v2
	v_lshl_add_u32 v198, s0, 7, v2
	s_waitcnt vmcnt(0)
	v_and_or_b32 v176, v0, 31, v198
	s_and_b32 s1, s12, 3
	v_readlane_b32 s2, v250, 8
	v_ashrrev_i32_e32 v177, 31, v176
	s_or_b32 s1, s1, s2
	v_lshl_add_u64 v[2:3], s[60:61], 0, v[176:177]
	v_readlane_b32 s2, v252, 56
	v_lshlrev_b64 v[4:5], 10, v[2:3]
	v_readlane_b32 s3, v252, 57
	v_bfe_u32 v196, v0, 5, 1
	s_lshl_b32 s80, s1, 6
	v_lshl_add_u64 v[4:5], s[2:3], 0, v[4:5]
	s_lshl_b32 s0, s1, 7
	s_mov_b32 s1, s81
	v_readlane_b32 s2, v252, 58
	v_lshl_add_u64 v[174:175], v[4:5], 0, s[0:1]
	v_lshlrev_b64 v[2:3], 9, v[2:3]
	v_lshlrev_b32_e32 v0, 4, v196
	v_readlane_b32 s3, v252, 59
	v_lshl_add_u64 v[4:5], v[174:175], 0, v[0:1]
	global_load_dwordx4 v[114:117], v[4:5], off
	global_load_dwordx4 v[146:149], v[4:5], off offset:32
	global_load_dwordx4 v[142:145], v[4:5], off offset:64
	global_load_dwordx4 v[138:141], v[4:5], off offset:96
	v_lshl_add_u64 v[2:3], s[2:3], 0, v[2:3]
	v_lshl_add_u64 v[2:3], v[2:3], 0, s[80:81]
	v_lshl_add_u64 v[2:3], v[2:3], 0, v[0:1]
	global_load_dwordx4 v[134:137], v[2:3], off
	global_load_dwordx4 v[130:133], v[2:3], off offset:32
	v_mov_b32_e32 v36, v222
	s_mov_b32 s2, 0x2aaaaaab
	v_readlane_b32 s1, v252, 60
	v_mul_hi_i32 v0, v36, s2
	v_lshrrev_b32_e32 v2, 31, v0
	v_ashrrev_i32_e32 v0, 1, v0
	v_add_u32_e32 v20, v0, v2
	v_mul_lo_u32 v0, v20, 12
	s_add_u32 s0, s1, s0
	v_readlane_b32 s1, v252, 61
	v_sub_u32_e32 v0, v36, v0
	v_ashrrev_i32_e32 v21, 31, v20
	s_addc_u32 s1, s1, 0
	v_cmp_gt_i32_e64 s[4:5], 8, v0
	v_cmp_lt_i32_e32 vcc, 7, v0
	v_lshlrev_b32_e32 v12, 3, v0
	v_lshlrev_b64 v[10:11], 6, v[20:21]
	s_barrier
	s_and_saveexec_b64 s[2:3], vcc
	s_xor_b64 s[2:3], exec, s[2:3]
	s_cbranch_execz .LBB0_238
	v_readlane_b32 s6, v252, 62
	v_readlane_b32 s7, v252, 63
	v_mov_b32_e32 v13, v1
	s_nop 0
	v_lshl_add_u64 v[2:3], s[6:7], 0, v[10:11]
	s_movk_i32 s6, 0xff80
	v_lshl_add_u64 v[2:3], v[12:13], 1, v[2:3]
	s_mov_b32 s7, -1
	v_lshl_add_u64 v[2:3], v[2:3], 0, s[6:7]
